# Win GEMM: row-scale sums and bias prefetched in the peeled first K-iteration, no epilogue table-build barrier; dropped per-iteration vmcnt(0) in the Win K-loop body
# baseline (speedup 1.0000x reference)
.LBB0_633:
	s_ashr_i32 s13, s12, 31
	s_lshl_b64 s[14:15], s[12:13], 19
	s_add_u32 s14, s37, s14
	s_addc_u32 s15, s42, s15
	s_and_b64 s[16:17], s[4:5], exec
	s_cselect_b32 s13, s15, s23
	s_cselect_b32 s19, s14, s22
	s_ashr_i32 s11, s10, 31
	s_lshl_b64 s[16:17], s[10:11], 19
	s_add_u32 s16, s29, s16
	s_addc_u32 s17, s43, s17
	s_and_b64 s[24:25], s[4:5], exec
	s_cselect_b32 s11, s17, s21
	s_cselect_b32 s60, s16, s20
	s_add_u32 s61, s20, 0x100
	s_addc_u32 s62, s21, 0
	s_add_u32 s20, s22, 0x40080
	s_addc_u32 s21, s23, 0
	s_mov_b32 s63, -2
	s_add_u32 s22, s20, 0xfffc0080
	s_addc_u32 s23, s21, -1
	s_add_i32 s64, 0, 0x10000
	s_cmp_eq_u32 s63, 12
	s_cselect_b32 s25, s13, s23
	s_cselect_b32 s24, s19, s22
	s_cselect_b32 s23, s11, s62
	s_cselect_b32 s22, s60, s61
	s_add_i32 s68, 0, 0x14000
	s_waitcnt vmcnt(0) lgkmcnt(0)
	s_lshl_b32 s74, s18, 8
	v_add_u32_e32 v178, s74, v182
	v_ashrrev_i32_e32 v179, 31, v178
	v_lshlrev_b64 v[178:179], 6, v[178:179]
	v_lshl_add_u64 v[178:179], s[70:71], 0, v[178:179]
	s_and_saveexec_b64 s[78:79], s[2:3]
	global_load_dwordx4 v[238:241], v[178:179], off
	global_load_dwordx4 v[242:245], v[178:179], off offset:16
	global_load_dwordx4 v[246:249], v[178:179], off offset:32
	global_load_dwordx4 v[250:253], v[178:179], off offset:48
	s_mov_b64 exec, s[78:79]
	v_add_u32_e32 v140, s64, v175
	v_add_u32_e32 v170, s68, v175
	ds_read_b128 v[128:131], v140
	ds_read_b128 v[132:135], v140 offset:1024
	ds_read_b128 v[136:139], v140 offset:2048
	ds_read_b128 v[140:143], v140 offset:3072
	ds_read_b128 v[144:147], v170
	ds_read_b128 v[162:165], v170 offset:1024
	ds_read_b128 v[166:169], v170 offset:2048
	ds_read_b128 v[170:173], v170 offset:3072
	v_lshl_add_u64 v[220:221], s[20:21], 0, v[160:161]
	s_add_i32 m0, s50, 0xc000
	ds_read_b128 v[186:189], v185
	ds_read_b128 v[190:193], v185 offset:1024
	ds_read_b128 v[194:197], v185 offset:2048
	ds_read_b128 v[198:201], v185 offset:3072
	ds_read_b128 v[202:205], v185 offset:4096
	ds_read_b128 v[206:209], v185 offset:5120
	ds_read_b128 v[210:213], v185 offset:6144
	ds_read_b128 v[228:231], v185 offset:7168
	global_load_lds_dwordx4 v[220:221], off
	v_lshl_add_u64 v[220:221], s[20:21], 0, v[158:159]
	s_add_i32 m0, s50, 0xe000
	s_nop 0
	global_load_lds_dwordx4 v[220:221], off
	s_waitcnt vmcnt(8)
	s_waitcnt lgkmcnt(0)
	s_barrier
	s_setprio 1
	v_mfma_f32_16x16x32_bf16 v[124:127], v[128:131], v[186:189], 0
	v_mfma_f32_16x16x32_bf16 v[120:123], v[136:139], v[186:189], 0
	v_mfma_f32_16x16x32_bf16 v[108:111], v[128:131], v[194:197], 0
	v_mfma_f32_16x16x32_bf16 v[104:107], v[136:139], v[194:197], 0
	v_mfma_f32_16x16x32_bf16 v[92:95], v[128:131], v[202:205], 0
	v_mfma_f32_16x16x32_bf16 v[88:91], v[136:139], v[202:205], 0
	v_mfma_f32_16x16x32_bf16 v[76:79], v[128:131], v[210:213], 0
	v_mfma_f32_16x16x32_bf16 v[72:75], v[136:139], v[210:213], 0
	v_mfma_f32_16x16x32_bf16 v[124:127], v[132:135], v[190:193], v[124:127]
	v_mfma_f32_16x16x32_bf16 v[120:123], v[140:143], v[190:193], v[120:123]
	v_mfma_f32_16x16x32_bf16 v[108:111], v[132:135], v[198:201], v[108:111]
	v_mfma_f32_16x16x32_bf16 v[104:107], v[140:143], v[198:201], v[104:107]
	v_mfma_f32_16x16x32_bf16 v[92:95], v[132:135], v[206:209], v[92:95]
	v_mfma_f32_16x16x32_bf16 v[88:91], v[140:143], v[206:209], v[88:91]
	v_mfma_f32_16x16x32_bf16 v[76:79], v[132:135], v[228:231], v[76:79]
	v_mfma_f32_16x16x32_bf16 v[72:75], v[140:143], v[228:231], v[72:75]
	v_mfma_f32_16x16x32_bf16 v[116:119], v[144:147], v[186:189], 0
	v_mfma_f32_16x16x32_bf16 v[112:115], v[166:169], v[186:189], 0
	v_mfma_f32_16x16x32_bf16 v[100:103], v[144:147], v[194:197], 0
	v_mfma_f32_16x16x32_bf16 v[96:99], v[166:169], v[194:197], 0
	v_mfma_f32_16x16x32_bf16 v[84:87], v[144:147], v[202:205], 0
	v_mfma_f32_16x16x32_bf16 v[80:83], v[166:169], v[202:205], 0
	v_mfma_f32_16x16x32_bf16 v[68:71], v[144:147], v[210:213], 0
	v_mfma_f32_16x16x32_bf16 v[64:67], v[166:169], v[210:213], 0
	v_mfma_f32_16x16x32_bf16 v[116:119], v[162:165], v[190:193], v[116:119]
	v_mfma_f32_16x16x32_bf16 v[112:115], v[170:173], v[190:193], v[112:115]
	v_mfma_f32_16x16x32_bf16 v[100:103], v[162:165], v[198:201], v[100:103]
	v_mfma_f32_16x16x32_bf16 v[96:99], v[170:173], v[198:201], v[96:99]
	s_setprio 2
	s_barrier
	v_mfma_f32_16x16x32_bf16 v[84:87], v[162:165], v[206:209], v[84:87]
	v_mfma_f32_16x16x32_bf16 v[80:83], v[170:173], v[206:209], v[80:83]
	v_mfma_f32_16x16x32_bf16 v[68:71], v[162:165], v[228:231], v[68:71]
	v_mfma_f32_16x16x32_bf16 v[64:67], v[170:173], v[228:231], v[64:67]
	s_setprio 0
	s_add_i32 s64, s64, s46
	v_lshl_add_u64 v[220:221], s[22:23], 0, v[152:153]
	s_mov_b32 m0, s64
	ds_read_b128 v[186:189], v185 offset:16384
	ds_read_b128 v[190:193], v185 offset:17408
	ds_read_b128 v[194:197], v185 offset:18432
	ds_read_b128 v[198:201], v185 offset:19456
	ds_read_b128 v[202:205], v185 offset:20480
	ds_read_b128 v[206:209], v185 offset:21504
	ds_read_b128 v[210:213], v185 offset:22528
	ds_read_b128 v[228:231], v185 offset:23552
	global_load_lds_dwordx4 v[220:221], off
	s_add_i32 m0, s64, 0x2000
	s_add_u32 s64, s22, 0x40000
	v_lshl_add_u64 v[222:223], s[22:23], 0, v[148:149]
	s_addc_u32 s65, s23, 0
	s_add_i32 s68, s68, s46
	global_load_lds_dwordx4 v[222:223], off
	v_lshl_add_u64 v[226:227], s[64:65], 0, v[152:153]
	s_mov_b32 m0, s68
	v_lshl_add_u64 v[232:233], s[24:25], 0, v[150:151]
	global_load_lds_dwordx4 v[226:227], off
	v_lshl_add_u64 v[226:227], s[64:65], 0, v[148:149]
	s_add_i32 m0, s68, 0x2000
	s_nop 0
	global_load_lds_dwordx4 v[226:227], off
	v_lshl_add_u64 v[226:227], s[24:25], 0, v[154:155]
	s_mov_b32 m0, s50
	s_nop 0
	global_load_lds_dwordx4 v[226:227], off
	s_mov_b32 m0, s51
	s_nop 0
	global_load_lds_dwordx4 v[232:233], off
	s_waitcnt vmcnt(8)
	s_waitcnt lgkmcnt(0)
	s_barrier
	s_setprio 1
	v_mfma_f32_16x16x32_bf16 v[60:63], v[128:131], v[186:189], 0
	v_mfma_f32_16x16x32_bf16 v[56:59], v[136:139], v[186:189], 0
	v_mfma_f32_16x16x32_bf16 v[48:51], v[128:131], v[194:197], 0
	v_mfma_f32_16x16x32_bf16 v[40:43], v[136:139], v[194:197], 0
	v_mfma_f32_16x16x32_bf16 v[32:35], v[128:131], v[202:205], 0
	v_mfma_f32_16x16x32_bf16 v[24:27], v[136:139], v[202:205], 0
	v_mfma_f32_16x16x32_bf16 v[16:19], v[128:131], v[210:213], 0
	v_mfma_f32_16x16x32_bf16 v[8:11], v[136:139], v[210:213], 0
	v_mfma_f32_16x16x32_bf16 v[60:63], v[132:135], v[190:193], v[60:63]
	v_mfma_f32_16x16x32_bf16 v[56:59], v[140:143], v[190:193], v[56:59]
	v_mfma_f32_16x16x32_bf16 v[48:51], v[132:135], v[198:201], v[48:51]
	v_mfma_f32_16x16x32_bf16 v[40:43], v[140:143], v[198:201], v[40:43]
	v_mfma_f32_16x16x32_bf16 v[32:35], v[132:135], v[206:209], v[32:35]
	v_mfma_f32_16x16x32_bf16 v[24:27], v[140:143], v[206:209], v[24:27]
	v_mfma_f32_16x16x32_bf16 v[16:19], v[132:135], v[228:231], v[16:19]
	v_mfma_f32_16x16x32_bf16 v[8:11], v[140:143], v[228:231], v[8:11]
	v_mfma_f32_16x16x32_bf16 v[52:55], v[144:147], v[186:189], 0
	v_mfma_f32_16x16x32_bf16 v[44:47], v[166:169], v[186:189], 0
	v_mfma_f32_16x16x32_bf16 v[36:39], v[144:147], v[194:197], 0
	v_mfma_f32_16x16x32_bf16 v[28:31], v[166:169], v[194:197], 0
	v_mfma_f32_16x16x32_bf16 v[20:23], v[144:147], v[202:205], 0
	v_mfma_f32_16x16x32_bf16 v[12:15], v[166:169], v[202:205], 0
	v_mfma_f32_16x16x32_bf16 v[4:7], v[144:147], v[210:213], 0
	v_mfma_f32_16x16x32_bf16 v[0:3], v[166:169], v[210:213], 0
	v_mfma_f32_16x16x32_bf16 v[52:55], v[162:165], v[190:193], v[52:55]
	v_mfma_f32_16x16x32_bf16 v[44:47], v[170:173], v[190:193], v[44:47]
	v_mfma_f32_16x16x32_bf16 v[36:39], v[162:165], v[198:201], v[36:39]
	v_mfma_f32_16x16x32_bf16 v[28:31], v[170:173], v[198:201], v[28:31]
	s_setprio 2
	s_barrier
	v_mfma_f32_16x16x32_bf16 v[20:23], v[162:165], v[206:209], v[20:23]
	v_mfma_f32_16x16x32_bf16 v[12:15], v[170:173], v[206:209], v[12:15]
	v_mfma_f32_16x16x32_bf16 v[4:7], v[162:165], v[228:231], v[4:7]
	v_mfma_f32_16x16x32_bf16 v[0:3], v[170:173], v[228:231], v[0:3]
	s_setprio 0
	s_and_saveexec_b64 s[78:79], s[2:3]
	v_add_f32_e32 v238, v238, v239
	v_add_f32_e32 v240, v240, v241
	v_add_f32_e32 v242, v242, v243
	v_add_f32_e32 v244, v244, v245
	v_add_f32_e32 v246, v246, v247
	v_add_f32_e32 v248, v248, v249
	v_add_f32_e32 v250, v250, v251
	v_add_f32_e32 v252, v252, v253
	v_add_f32_e32 v238, v238, v240
	v_add_f32_e32 v242, v242, v244
	v_add_f32_e32 v246, v246, v248
	v_add_f32_e32 v250, v250, v252
	v_add_f32_e32 v238, v238, v242
	v_add_f32_e32 v246, v246, v250
	v_add_f32_e32 v238, v238, v246
	v_fmamk_f32 v238, v238, 0x3a800000, v216
	v_rsq_f32_e32 v238, v238
	s_nop 0
	ds_write_b32 v183, v238
	s_mov_b64 exec, s[78:79]
	s_add_i32 s64, 0, 0x18000
	s_add_i32 s65, 0, 0x1c000
	v_add_u32_e32 v140, s64, v175
	v_add_u32_e32 v170, s65, v175
	ds_read_b128 v[128:131], v140
	ds_read_b128 v[132:135], v140 offset:1024
	ds_read_b128 v[136:139], v140 offset:2048
	ds_read_b128 v[140:143], v140 offset:3072
	ds_read_b128 v[144:147], v170
	ds_read_b128 v[162:165], v170 offset:1024
	ds_read_b128 v[166:169], v170 offset:2048
	ds_read_b128 v[170:173], v170 offset:3072
	s_add_u32 s24, s24, 0x40000
	s_addc_u32 s25, s25, 0
	s_mov_b32 m0, s52
	v_lshl_add_u64 v[234:235], s[24:25], 0, v[154:155]
	ds_read_b128 v[186:189], v185 offset:32768
	ds_read_b128 v[190:193], v185 offset:33792
	ds_read_b128 v[194:197], v185 offset:34816
	ds_read_b128 v[198:201], v185 offset:35840
	ds_read_b128 v[202:205], v185 offset:36864
	ds_read_b128 v[206:209], v185 offset:37888
	ds_read_b128 v[210:213], v185 offset:38912
	ds_read_b128 v[228:231], v185 offset:39936
	global_load_lds_dwordx4 v[234:235], off
	v_lshl_add_u64 v[234:235], s[24:25], 0, v[150:151]
	s_mov_b32 m0, s53
	s_nop 0
	global_load_lds_dwordx4 v[234:235], off
	s_waitcnt vmcnt(8)
	s_waitcnt lgkmcnt(0)
	s_barrier
	s_setprio 1
	v_mfma_f32_16x16x32_bf16 v[124:127], v[128:131], v[186:189], v[124:127]
	v_mfma_f32_16x16x32_bf16 v[120:123], v[136:139], v[186:189], v[120:123]
	v_mfma_f32_16x16x32_bf16 v[108:111], v[128:131], v[194:197], v[108:111]
	v_mfma_f32_16x16x32_bf16 v[104:107], v[136:139], v[194:197], v[104:107]
	v_mfma_f32_16x16x32_bf16 v[92:95], v[128:131], v[202:205], v[92:95]
	v_mfma_f32_16x16x32_bf16 v[88:91], v[136:139], v[202:205], v[88:91]
	v_mfma_f32_16x16x32_bf16 v[76:79], v[128:131], v[210:213], v[76:79]
	v_mfma_f32_16x16x32_bf16 v[72:75], v[136:139], v[210:213], v[72:75]
	v_mfma_f32_16x16x32_bf16 v[124:127], v[132:135], v[190:193], v[124:127]
	v_mfma_f32_16x16x32_bf16 v[120:123], v[140:143], v[190:193], v[120:123]
	v_mfma_f32_16x16x32_bf16 v[108:111], v[132:135], v[198:201], v[108:111]
	v_mfma_f32_16x16x32_bf16 v[104:107], v[140:143], v[198:201], v[104:107]
	v_mfma_f32_16x16x32_bf16 v[92:95], v[132:135], v[206:209], v[92:95]
	v_mfma_f32_16x16x32_bf16 v[88:91], v[140:143], v[206:209], v[88:91]
	v_mfma_f32_16x16x32_bf16 v[76:79], v[132:135], v[228:231], v[76:79]
	v_mfma_f32_16x16x32_bf16 v[72:75], v[140:143], v[228:231], v[72:75]
	v_mfma_f32_16x16x32_bf16 v[116:119], v[144:147], v[186:189], v[116:119]
	v_mfma_f32_16x16x32_bf16 v[112:115], v[166:169], v[186:189], v[112:115]
	v_mfma_f32_16x16x32_bf16 v[100:103], v[144:147], v[194:197], v[100:103]
	v_mfma_f32_16x16x32_bf16 v[96:99], v[166:169], v[194:197], v[96:99]
	v_mfma_f32_16x16x32_bf16 v[84:87], v[144:147], v[202:205], v[84:87]
	v_mfma_f32_16x16x32_bf16 v[80:83], v[166:169], v[202:205], v[80:83]
	v_mfma_f32_16x16x32_bf16 v[68:71], v[144:147], v[210:213], v[68:71]
	v_mfma_f32_16x16x32_bf16 v[64:67], v[166:169], v[210:213], v[64:67]
	v_mfma_f32_16x16x32_bf16 v[116:119], v[162:165], v[190:193], v[116:119]
	v_mfma_f32_16x16x32_bf16 v[112:115], v[170:173], v[190:193], v[112:115]
	v_mfma_f32_16x16x32_bf16 v[100:103], v[162:165], v[198:201], v[100:103]
	v_mfma_f32_16x16x32_bf16 v[96:99], v[170:173], v[198:201], v[96:99]
	s_setprio 2
	s_barrier
	v_mfma_f32_16x16x32_bf16 v[84:87], v[162:165], v[206:209], v[84:87]
	v_mfma_f32_16x16x32_bf16 v[80:83], v[170:173], v[206:209], v[80:83]
	v_mfma_f32_16x16x32_bf16 v[68:71], v[162:165], v[228:231], v[68:71]
	v_mfma_f32_16x16x32_bf16 v[64:67], v[170:173], v[228:231], v[64:67]
	s_setprio 0
	s_min_i32 s74, s18, 0x80
	s_ashr_i32 s74, s74, 3
	s_mul_hi_i32 s75, s74, 0x3000
	s_mulk_i32 s74, 0x3000
	s_add_u32 s74, s54, s74
	s_addc_u32 s75, s55, s75
	s_lshl_b32 s76, s44, 8
	s_ashr_i32 s77, s76, 31
	s_lshl_b64 s[76:77], s[76:77], 2
	s_add_u32 s74, s74, s76
	s_addc_u32 s75, s75, s77
	v_lshl_add_u64 v[178:179], s[74:75], 0, v[176:177]
	global_load_dwordx4 v[238:241], v[178:179], off
	global_load_dwordx4 v[242:245], v[178:179], off offset:16
	global_load_dwordx4 v[246:249], v[178:179], off offset:512
	global_load_dwordx4 v[250:253], v[178:179], off offset:528
	s_add_i32 s24, s64, s46
	v_lshl_add_u64 v[220:221], v[220:221], 0, s[34:35]
	s_mov_b32 m0, s24
	ds_read_b128 v[186:189], v185 offset:49152
	ds_read_b128 v[190:193], v185 offset:50176
	ds_read_b128 v[194:197], v185 offset:51200
	ds_read_b128 v[198:201], v185 offset:52224
	ds_read_b128 v[202:205], v185 offset:53248
	ds_read_b128 v[206:209], v185 offset:54272
	ds_read_b128 v[210:213], v185 offset:55296
	ds_read_b128 v[228:231], v185 offset:56320
	global_load_lds_dwordx4 v[220:221], off
	s_add_i32 m0, s24, 0x2000
	s_add_u32 s22, s22, 0x40080
	v_lshl_add_u64 v[220:221], v[222:223], 0, s[34:35]
	s_addc_u32 s23, s23, 0
	s_add_i32 s24, s65, s46
	global_load_lds_dwordx4 v[220:221], off
	v_lshl_add_u64 v[220:221], s[22:23], 0, v[152:153]
	s_mov_b32 m0, s24
	s_nop 0
	global_load_lds_dwordx4 v[220:221], off
	v_lshl_add_u64 v[220:221], s[22:23], 0, v[148:149]
	s_add_i32 m0, s24, 0x2000
	s_nop 0
	global_load_lds_dwordx4 v[220:221], off
	v_lshl_add_u64 v[220:221], v[226:227], 0, s[34:35]
	s_mov_b32 m0, s56
	s_nop 0
	global_load_lds_dwordx4 v[220:221], off
	v_lshl_add_u64 v[220:221], v[232:233], 0, s[34:35]
	s_mov_b32 m0, s57
	s_nop 0
	global_load_lds_dwordx4 v[220:221], off
	s_waitcnt vmcnt(12)
	s_waitcnt lgkmcnt(0)
	s_barrier
	s_setprio 1
	v_mfma_f32_16x16x32_bf16 v[60:63], v[128:131], v[186:189], v[60:63]
	v_mfma_f32_16x16x32_bf16 v[56:59], v[136:139], v[186:189], v[56:59]
	v_mfma_f32_16x16x32_bf16 v[48:51], v[128:131], v[194:197], v[48:51]
	v_mfma_f32_16x16x32_bf16 v[40:43], v[136:139], v[194:197], v[40:43]
	v_mfma_f32_16x16x32_bf16 v[32:35], v[128:131], v[202:205], v[32:35]
	v_mfma_f32_16x16x32_bf16 v[24:27], v[136:139], v[202:205], v[24:27]
	v_mfma_f32_16x16x32_bf16 v[16:19], v[128:131], v[210:213], v[16:19]
	v_mfma_f32_16x16x32_bf16 v[8:11], v[136:139], v[210:213], v[8:11]
	v_mfma_f32_16x16x32_bf16 v[60:63], v[132:135], v[190:193], v[60:63]
	v_mfma_f32_16x16x32_bf16 v[56:59], v[140:143], v[190:193], v[56:59]
	v_mfma_f32_16x16x32_bf16 v[48:51], v[132:135], v[198:201], v[48:51]
	v_mfma_f32_16x16x32_bf16 v[40:43], v[140:143], v[198:201], v[40:43]
	v_mfma_f32_16x16x32_bf16 v[32:35], v[132:135], v[206:209], v[32:35]
	v_mfma_f32_16x16x32_bf16 v[24:27], v[140:143], v[206:209], v[24:27]
	v_mfma_f32_16x16x32_bf16 v[16:19], v[132:135], v[228:231], v[16:19]
	v_mfma_f32_16x16x32_bf16 v[8:11], v[140:143], v[228:231], v[8:11]
	v_mfma_f32_16x16x32_bf16 v[52:55], v[144:147], v[186:189], v[52:55]
	v_mfma_f32_16x16x32_bf16 v[44:47], v[166:169], v[186:189], v[44:47]
	v_mfma_f32_16x16x32_bf16 v[36:39], v[144:147], v[194:197], v[36:39]
	v_mfma_f32_16x16x32_bf16 v[28:31], v[166:169], v[194:197], v[28:31]
	v_mfma_f32_16x16x32_bf16 v[20:23], v[144:147], v[202:205], v[20:23]
	v_mfma_f32_16x16x32_bf16 v[12:15], v[166:169], v[202:205], v[12:15]
	v_mfma_f32_16x16x32_bf16 v[4:7], v[144:147], v[210:213], v[4:7]
	v_mfma_f32_16x16x32_bf16 v[0:3], v[166:169], v[210:213], v[0:3]
	v_mfma_f32_16x16x32_bf16 v[52:55], v[162:165], v[190:193], v[52:55]
	v_mfma_f32_16x16x32_bf16 v[44:47], v[170:173], v[190:193], v[44:47]
	v_mfma_f32_16x16x32_bf16 v[36:39], v[162:165], v[198:201], v[36:39]
	v_mfma_f32_16x16x32_bf16 v[28:31], v[170:173], v[198:201], v[28:31]
	s_setprio 2
	s_barrier
	v_mfma_f32_16x16x32_bf16 v[20:23], v[162:165], v[206:209], v[20:23]
	v_mfma_f32_16x16x32_bf16 v[12:15], v[170:173], v[206:209], v[12:15]
	v_mfma_f32_16x16x32_bf16 v[4:7], v[162:165], v[228:231], v[4:7]
	v_mfma_f32_16x16x32_bf16 v[0:3], v[170:173], v[228:231], v[0:3]
	s_setprio 0
	s_add_i32 s63, s63, 2
	s_add_u32 s61, s61, 0x100
	s_addc_u32 s62, s62, 0
	s_add_u32 s20, s20, 0x100
	s_addc_u32 s21, s21, 0
	s_cmp_gt_u32 s63, 13
	s_cbranch_scc1 .Lpeel_exit_1
.LBB0_634:
	s_add_u32 s22, s20, 0xfffc0080
	s_addc_u32 s23, s21, -1
	s_add_i32 s64, 0, 0x10000
	s_cmp_eq_u32 s63, 12
	s_cselect_b32 s25, s13, s23
	s_cselect_b32 s24, s19, s22
	s_cselect_b32 s23, s11, s62
	s_cselect_b32 s22, s60, s61
	s_add_i32 s68, 0, 0x14000
	s_waitcnt lgkmcnt(0)
	v_add_u32_e32 v140, s64, v175
	v_add_u32_e32 v170, s68, v175
	ds_read_b128 v[128:131], v140
	ds_read_b128 v[132:135], v140 offset:1024
	ds_read_b128 v[136:139], v140 offset:2048
	ds_read_b128 v[140:143], v140 offset:3072
	ds_read_b128 v[144:147], v170
	ds_read_b128 v[162:165], v170 offset:1024
	ds_read_b128 v[166:169], v170 offset:2048
	ds_read_b128 v[170:173], v170 offset:3072
	v_lshl_add_u64 v[220:221], s[20:21], 0, v[160:161]
	s_add_i32 m0, s50, 0xc000
	ds_read_b128 v[186:189], v185
	ds_read_b128 v[190:193], v185 offset:1024
	ds_read_b128 v[194:197], v185 offset:2048
	ds_read_b128 v[198:201], v185 offset:3072
	ds_read_b128 v[202:205], v185 offset:4096
	ds_read_b128 v[206:209], v185 offset:5120
	ds_read_b128 v[210:213], v185 offset:6144
	ds_read_b128 v[228:231], v185 offset:7168
	global_load_lds_dwordx4 v[220:221], off
	v_lshl_add_u64 v[220:221], s[20:21], 0, v[158:159]
	s_add_i32 m0, s50, 0xe000
	s_nop 0
	global_load_lds_dwordx4 v[220:221], off
	s_waitcnt vmcnt(8)
	s_waitcnt lgkmcnt(0)
	s_barrier
	s_setprio 1
	v_mfma_f32_16x16x32_bf16 v[124:127], v[128:131], v[186:189], v[124:127]
	v_mfma_f32_16x16x32_bf16 v[120:123], v[136:139], v[186:189], v[120:123]
	v_mfma_f32_16x16x32_bf16 v[108:111], v[128:131], v[194:197], v[108:111]
	v_mfma_f32_16x16x32_bf16 v[104:107], v[136:139], v[194:197], v[104:107]
	v_mfma_f32_16x16x32_bf16 v[92:95], v[128:131], v[202:205], v[92:95]
	v_mfma_f32_16x16x32_bf16 v[88:91], v[136:139], v[202:205], v[88:91]
	v_mfma_f32_16x16x32_bf16 v[76:79], v[128:131], v[210:213], v[76:79]
	v_mfma_f32_16x16x32_bf16 v[72:75], v[136:139], v[210:213], v[72:75]
	v_mfma_f32_16x16x32_bf16 v[124:127], v[132:135], v[190:193], v[124:127]
	v_mfma_f32_16x16x32_bf16 v[120:123], v[140:143], v[190:193], v[120:123]
	v_mfma_f32_16x16x32_bf16 v[108:111], v[132:135], v[198:201], v[108:111]
	v_mfma_f32_16x16x32_bf16 v[104:107], v[140:143], v[198:201], v[104:107]
	v_mfma_f32_16x16x32_bf16 v[92:95], v[132:135], v[206:209], v[92:95]
	v_mfma_f32_16x16x32_bf16 v[88:91], v[140:143], v[206:209], v[88:91]
	v_mfma_f32_16x16x32_bf16 v[76:79], v[132:135], v[228:231], v[76:79]
	v_mfma_f32_16x16x32_bf16 v[72:75], v[140:143], v[228:231], v[72:75]
	v_mfma_f32_16x16x32_bf16 v[116:119], v[144:147], v[186:189], v[116:119]
	v_mfma_f32_16x16x32_bf16 v[112:115], v[166:169], v[186:189], v[112:115]
	v_mfma_f32_16x16x32_bf16 v[100:103], v[144:147], v[194:197], v[100:103]
	v_mfma_f32_16x16x32_bf16 v[96:99], v[166:169], v[194:197], v[96:99]
	v_mfma_f32_16x16x32_bf16 v[84:87], v[144:147], v[202:205], v[84:87]
	v_mfma_f32_16x16x32_bf16 v[80:83], v[166:169], v[202:205], v[80:83]
	v_mfma_f32_16x16x32_bf16 v[68:71], v[144:147], v[210:213], v[68:71]
	v_mfma_f32_16x16x32_bf16 v[64:67], v[166:169], v[210:213], v[64:67]
	v_mfma_f32_16x16x32_bf16 v[116:119], v[162:165], v[190:193], v[116:119]
	v_mfma_f32_16x16x32_bf16 v[112:115], v[170:173], v[190:193], v[112:115]
	v_mfma_f32_16x16x32_bf16 v[100:103], v[162:165], v[198:201], v[100:103]
	v_mfma_f32_16x16x32_bf16 v[96:99], v[170:173], v[198:201], v[96:99]
	s_setprio 2
	s_barrier
	v_mfma_f32_16x16x32_bf16 v[84:87], v[162:165], v[206:209], v[84:87]
	v_mfma_f32_16x16x32_bf16 v[80:83], v[170:173], v[206:209], v[80:83]
	v_mfma_f32_16x16x32_bf16 v[68:71], v[162:165], v[228:231], v[68:71]
	v_mfma_f32_16x16x32_bf16 v[64:67], v[170:173], v[228:231], v[64:67]
	s_setprio 0
	s_add_i32 s64, s64, s46
	v_lshl_add_u64 v[220:221], s[22:23], 0, v[152:153]
	s_mov_b32 m0, s64
	ds_read_b128 v[186:189], v185 offset:16384
	ds_read_b128 v[190:193], v185 offset:17408
	ds_read_b128 v[194:197], v185 offset:18432
	ds_read_b128 v[198:201], v185 offset:19456
	ds_read_b128 v[202:205], v185 offset:20480
	ds_read_b128 v[206:209], v185 offset:21504
	ds_read_b128 v[210:213], v185 offset:22528
	ds_read_b128 v[228:231], v185 offset:23552
	global_load_lds_dwordx4 v[220:221], off
	s_add_i32 m0, s64, 0x2000
	s_add_u32 s64, s22, 0x40000
	v_lshl_add_u64 v[222:223], s[22:23], 0, v[148:149]
	s_addc_u32 s65, s23, 0
	s_add_i32 s68, s68, s46
	global_load_lds_dwordx4 v[222:223], off
	v_lshl_add_u64 v[226:227], s[64:65], 0, v[152:153]
	s_mov_b32 m0, s68
	v_lshl_add_u64 v[232:233], s[24:25], 0, v[150:151]
	global_load_lds_dwordx4 v[226:227], off
	v_lshl_add_u64 v[226:227], s[64:65], 0, v[148:149]
	s_add_i32 m0, s68, 0x2000
	s_nop 0
	global_load_lds_dwordx4 v[226:227], off
	v_lshl_add_u64 v[226:227], s[24:25], 0, v[154:155]
	s_mov_b32 m0, s50
	s_nop 0
	global_load_lds_dwordx4 v[226:227], off
	s_mov_b32 m0, s51
	s_nop 0
	global_load_lds_dwordx4 v[232:233], off
	s_waitcnt vmcnt(8)
	s_waitcnt lgkmcnt(0)
	s_barrier
	s_setprio 1
	v_mfma_f32_16x16x32_bf16 v[60:63], v[128:131], v[186:189], v[60:63]
	v_mfma_f32_16x16x32_bf16 v[56:59], v[136:139], v[186:189], v[56:59]
	v_mfma_f32_16x16x32_bf16 v[48:51], v[128:131], v[194:197], v[48:51]
	v_mfma_f32_16x16x32_bf16 v[40:43], v[136:139], v[194:197], v[40:43]
	v_mfma_f32_16x16x32_bf16 v[32:35], v[128:131], v[202:205], v[32:35]
	v_mfma_f32_16x16x32_bf16 v[24:27], v[136:139], v[202:205], v[24:27]
	v_mfma_f32_16x16x32_bf16 v[16:19], v[128:131], v[210:213], v[16:19]
	v_mfma_f32_16x16x32_bf16 v[8:11], v[136:139], v[210:213], v[8:11]
	v_mfma_f32_16x16x32_bf16 v[60:63], v[132:135], v[190:193], v[60:63]
	v_mfma_f32_16x16x32_bf16 v[56:59], v[140:143], v[190:193], v[56:59]
	v_mfma_f32_16x16x32_bf16 v[48:51], v[132:135], v[198:201], v[48:51]
	v_mfma_f32_16x16x32_bf16 v[40:43], v[140:143], v[198:201], v[40:43]
	v_mfma_f32_16x16x32_bf16 v[32:35], v[132:135], v[206:209], v[32:35]
	v_mfma_f32_16x16x32_bf16 v[24:27], v[140:143], v[206:209], v[24:27]
	v_mfma_f32_16x16x32_bf16 v[16:19], v[132:135], v[228:231], v[16:19]
	v_mfma_f32_16x16x32_bf16 v[8:11], v[140:143], v[228:231], v[8:11]
	v_mfma_f32_16x16x32_bf16 v[52:55], v[144:147], v[186:189], v[52:55]
	v_mfma_f32_16x16x32_bf16 v[44:47], v[166:169], v[186:189], v[44:47]
	v_mfma_f32_16x16x32_bf16 v[36:39], v[144:147], v[194:197], v[36:39]
	v_mfma_f32_16x16x32_bf16 v[28:31], v[166:169], v[194:197], v[28:31]
	v_mfma_f32_16x16x32_bf16 v[20:23], v[144:147], v[202:205], v[20:23]
	v_mfma_f32_16x16x32_bf16 v[12:15], v[166:169], v[202:205], v[12:15]
	v_mfma_f32_16x16x32_bf16 v[4:7], v[144:147], v[210:213], v[4:7]
	v_mfma_f32_16x16x32_bf16 v[0:3], v[166:169], v[210:213], v[0:3]
	v_mfma_f32_16x16x32_bf16 v[52:55], v[162:165], v[190:193], v[52:55]
	v_mfma_f32_16x16x32_bf16 v[44:47], v[170:173], v[190:193], v[44:47]
	v_mfma_f32_16x16x32_bf16 v[36:39], v[162:165], v[198:201], v[36:39]
	v_mfma_f32_16x16x32_bf16 v[28:31], v[170:173], v[198:201], v[28:31]
	s_setprio 2
	s_barrier
	v_mfma_f32_16x16x32_bf16 v[20:23], v[162:165], v[206:209], v[20:23]
	v_mfma_f32_16x16x32_bf16 v[12:15], v[170:173], v[206:209], v[12:15]
	v_mfma_f32_16x16x32_bf16 v[4:7], v[162:165], v[228:231], v[4:7]
	v_mfma_f32_16x16x32_bf16 v[0:3], v[170:173], v[228:231], v[0:3]
	s_setprio 0
	s_add_i32 s64, 0, 0x18000
	s_add_i32 s65, 0, 0x1c000
	v_add_u32_e32 v140, s64, v175
	v_add_u32_e32 v170, s65, v175
	ds_read_b128 v[128:131], v140
	ds_read_b128 v[132:135], v140 offset:1024
	ds_read_b128 v[136:139], v140 offset:2048
	ds_read_b128 v[140:143], v140 offset:3072
	ds_read_b128 v[144:147], v170
	ds_read_b128 v[162:165], v170 offset:1024
	ds_read_b128 v[166:169], v170 offset:2048
	ds_read_b128 v[170:173], v170 offset:3072
	s_add_u32 s24, s24, 0x40000
	s_addc_u32 s25, s25, 0
	s_mov_b32 m0, s52
	v_lshl_add_u64 v[234:235], s[24:25], 0, v[154:155]
	ds_read_b128 v[186:189], v185 offset:32768
	ds_read_b128 v[190:193], v185 offset:33792
	ds_read_b128 v[194:197], v185 offset:34816
	ds_read_b128 v[198:201], v185 offset:35840
	ds_read_b128 v[202:205], v185 offset:36864
	ds_read_b128 v[206:209], v185 offset:37888
	ds_read_b128 v[210:213], v185 offset:38912
	ds_read_b128 v[228:231], v185 offset:39936
	global_load_lds_dwordx4 v[234:235], off
	v_lshl_add_u64 v[234:235], s[24:25], 0, v[150:151]
	s_mov_b32 m0, s53
	s_nop 0
	global_load_lds_dwordx4 v[234:235], off
	s_waitcnt vmcnt(8)
	s_waitcnt lgkmcnt(0)
	s_barrier
	s_setprio 1
	v_mfma_f32_16x16x32_bf16 v[124:127], v[128:131], v[186:189], v[124:127]
	v_mfma_f32_16x16x32_bf16 v[120:123], v[136:139], v[186:189], v[120:123]
	v_mfma_f32_16x16x32_bf16 v[108:111], v[128:131], v[194:197], v[108:111]
	v_mfma_f32_16x16x32_bf16 v[104:107], v[136:139], v[194:197], v[104:107]
	v_mfma_f32_16x16x32_bf16 v[92:95], v[128:131], v[202:205], v[92:95]
	v_mfma_f32_16x16x32_bf16 v[88:91], v[136:139], v[202:205], v[88:91]
	v_mfma_f32_16x16x32_bf16 v[76:79], v[128:131], v[210:213], v[76:79]
	v_mfma_f32_16x16x32_bf16 v[72:75], v[136:139], v[210:213], v[72:75]
	v_mfma_f32_16x16x32_bf16 v[124:127], v[132:135], v[190:193], v[124:127]
	v_mfma_f32_16x16x32_bf16 v[120:123], v[140:143], v[190:193], v[120:123]
	v_mfma_f32_16x16x32_bf16 v[108:111], v[132:135], v[198:201], v[108:111]
	v_mfma_f32_16x16x32_bf16 v[104:107], v[140:143], v[198:201], v[104:107]
	v_mfma_f32_16x16x32_bf16 v[92:95], v[132:135], v[206:209], v[92:95]
	v_mfma_f32_16x16x32_bf16 v[88:91], v[140:143], v[206:209], v[88:91]
	v_mfma_f32_16x16x32_bf16 v[76:79], v[132:135], v[228:231], v[76:79]
	v_mfma_f32_16x16x32_bf16 v[72:75], v[140:143], v[228:231], v[72:75]
	v_mfma_f32_16x16x32_bf16 v[116:119], v[144:147], v[186:189], v[116:119]
	v_mfma_f32_16x16x32_bf16 v[112:115], v[166:169], v[186:189], v[112:115]
	v_mfma_f32_16x16x32_bf16 v[100:103], v[144:147], v[194:197], v[100:103]
	v_mfma_f32_16x16x32_bf16 v[96:99], v[166:169], v[194:197], v[96:99]
	v_mfma_f32_16x16x32_bf16 v[84:87], v[144:147], v[202:205], v[84:87]
	v_mfma_f32_16x16x32_bf16 v[80:83], v[166:169], v[202:205], v[80:83]
	v_mfma_f32_16x16x32_bf16 v[68:71], v[144:147], v[210:213], v[68:71]
	v_mfma_f32_16x16x32_bf16 v[64:67], v[166:169], v[210:213], v[64:67]
	v_mfma_f32_16x16x32_bf16 v[116:119], v[162:165], v[190:193], v[116:119]
	v_mfma_f32_16x16x32_bf16 v[112:115], v[170:173], v[190:193], v[112:115]
	v_mfma_f32_16x16x32_bf16 v[100:103], v[162:165], v[198:201], v[100:103]
	v_mfma_f32_16x16x32_bf16 v[96:99], v[170:173], v[198:201], v[96:99]
	s_setprio 2
	s_barrier
	v_mfma_f32_16x16x32_bf16 v[84:87], v[162:165], v[206:209], v[84:87]
	v_mfma_f32_16x16x32_bf16 v[80:83], v[170:173], v[206:209], v[80:83]
	v_mfma_f32_16x16x32_bf16 v[68:71], v[162:165], v[228:231], v[68:71]
	v_mfma_f32_16x16x32_bf16 v[64:67], v[170:173], v[228:231], v[64:67]
	s_setprio 0
	s_add_i32 s24, s64, s46
	v_lshl_add_u64 v[220:221], v[220:221], 0, s[34:35]
	s_mov_b32 m0, s24
	ds_read_b128 v[186:189], v185 offset:49152
	ds_read_b128 v[190:193], v185 offset:50176
	ds_read_b128 v[194:197], v185 offset:51200
	ds_read_b128 v[198:201], v185 offset:52224
	ds_read_b128 v[202:205], v185 offset:53248
	ds_read_b128 v[206:209], v185 offset:54272
	ds_read_b128 v[210:213], v185 offset:55296
	ds_read_b128 v[228:231], v185 offset:56320
	global_load_lds_dwordx4 v[220:221], off
	s_add_i32 m0, s24, 0x2000
	s_add_u32 s22, s22, 0x40080
	v_lshl_add_u64 v[220:221], v[222:223], 0, s[34:35]
	s_addc_u32 s23, s23, 0
	s_add_i32 s24, s65, s46
	global_load_lds_dwordx4 v[220:221], off
	v_lshl_add_u64 v[220:221], s[22:23], 0, v[152:153]
	s_mov_b32 m0, s24
	s_nop 0
	global_load_lds_dwordx4 v[220:221], off
	v_lshl_add_u64 v[220:221], s[22:23], 0, v[148:149]
	s_add_i32 m0, s24, 0x2000
	s_nop 0
	global_load_lds_dwordx4 v[220:221], off
	v_lshl_add_u64 v[220:221], v[226:227], 0, s[34:35]
	s_mov_b32 m0, s56
	s_nop 0
	global_load_lds_dwordx4 v[220:221], off
	v_lshl_add_u64 v[220:221], v[232:233], 0, s[34:35]
	s_mov_b32 m0, s57
	s_nop 0
	global_load_lds_dwordx4 v[220:221], off
	s_waitcnt vmcnt(8)
	s_waitcnt lgkmcnt(0)
	s_barrier
	s_setprio 1
	v_mfma_f32_16x16x32_bf16 v[60:63], v[128:131], v[186:189], v[60:63]
	v_mfma_f32_16x16x32_bf16 v[56:59], v[136:139], v[186:189], v[56:59]
	v_mfma_f32_16x16x32_bf16 v[48:51], v[128:131], v[194:197], v[48:51]
	v_mfma_f32_16x16x32_bf16 v[40:43], v[136:139], v[194:197], v[40:43]
	v_mfma_f32_16x16x32_bf16 v[32:35], v[128:131], v[202:205], v[32:35]
	v_mfma_f32_16x16x32_bf16 v[24:27], v[136:139], v[202:205], v[24:27]
	v_mfma_f32_16x16x32_bf16 v[16:19], v[128:131], v[210:213], v[16:19]
	v_mfma_f32_16x16x32_bf16 v[8:11], v[136:139], v[210:213], v[8:11]
	v_mfma_f32_16x16x32_bf16 v[60:63], v[132:135], v[190:193], v[60:63]
	v_mfma_f32_16x16x32_bf16 v[56:59], v[140:143], v[190:193], v[56:59]
	v_mfma_f32_16x16x32_bf16 v[48:51], v[132:135], v[198:201], v[48:51]
	v_mfma_f32_16x16x32_bf16 v[40:43], v[140:143], v[198:201], v[40:43]
	v_mfma_f32_16x16x32_bf16 v[32:35], v[132:135], v[206:209], v[32:35]
	v_mfma_f32_16x16x32_bf16 v[24:27], v[140:143], v[206:209], v[24:27]
	v_mfma_f32_16x16x32_bf16 v[16:19], v[132:135], v[228:231], v[16:19]
	v_mfma_f32_16x16x32_bf16 v[8:11], v[140:143], v[228:231], v[8:11]
	v_mfma_f32_16x16x32_bf16 v[52:55], v[144:147], v[186:189], v[52:55]
	v_mfma_f32_16x16x32_bf16 v[44:47], v[166:169], v[186:189], v[44:47]
	v_mfma_f32_16x16x32_bf16 v[36:39], v[144:147], v[194:197], v[36:39]
	v_mfma_f32_16x16x32_bf16 v[28:31], v[166:169], v[194:197], v[28:31]
	v_mfma_f32_16x16x32_bf16 v[20:23], v[144:147], v[202:205], v[20:23]
	v_mfma_f32_16x16x32_bf16 v[12:15], v[166:169], v[202:205], v[12:15]
	v_mfma_f32_16x16x32_bf16 v[4:7], v[144:147], v[210:213], v[4:7]
	v_mfma_f32_16x16x32_bf16 v[0:3], v[166:169], v[210:213], v[0:3]
	v_mfma_f32_16x16x32_bf16 v[52:55], v[162:165], v[190:193], v[52:55]
	v_mfma_f32_16x16x32_bf16 v[44:47], v[170:173], v[190:193], v[44:47]
	v_mfma_f32_16x16x32_bf16 v[36:39], v[162:165], v[198:201], v[36:39]
	v_mfma_f32_16x16x32_bf16 v[28:31], v[170:173], v[198:201], v[28:31]
	s_setprio 2
	s_barrier
	v_mfma_f32_16x16x32_bf16 v[20:23], v[162:165], v[206:209], v[20:23]
	v_mfma_f32_16x16x32_bf16 v[12:15], v[170:173], v[206:209], v[12:15]
	v_mfma_f32_16x16x32_bf16 v[4:7], v[162:165], v[228:231], v[4:7]
	v_mfma_f32_16x16x32_bf16 v[0:3], v[170:173], v[228:231], v[0:3]
	s_setprio 0
	s_add_i32 s63, s63, 2
	s_add_u32 s61, s61, 0x100
	s_addc_u32 s62, s62, 0
	s_add_u32 s20, s20, 0x100
	s_addc_u32 s21, s21, 0
	s_cmp_gt_u32 s63, 13
	s_cbranch_scc0 .LBB0_634

.LBB0_637:
	s_lshl_b32 s11, s18, 8
	s_lshl_b32 s18, s44, 8
	s_ashr_i32 s19, s18, 31
	v_mov_b32_e32 v140, v238
	v_mov_b32_e32 v141, v239
	v_mov_b32_e32 v142, v240
	v_mov_b32_e32 v143, v241
	v_mov_b32_e32 v136, v242
	v_mov_b32_e32 v137, v243
	v_mov_b32_e32 v138, v244
	v_mov_b32_e32 v139, v245
	v_mov_b32_e32 v132, v246
	v_mov_b32_e32 v133, v247
	v_mov_b32_e32 v134, v248
	v_mov_b32_e32 v135, v249
	v_mov_b32_e32 v128, v250
	v_mov_b32_e32 v129, v251
	v_mov_b32_e32 v130, v252
	v_mov_b32_e32 v131, v253
	v_add_u32_e32 v170, s11, v157
	v_or_b32_e32 v168, 16, v170
	v_or_b32_e32 v166, 32, v170
	v_or_b32_e32 v164, 48, v170
	s_mov_b64 s[20:21], -1
	s_cmp_gt_i32 s44, 3
	v_ashrrev_i32_e32 v171, 31, v170
	v_lshlrev_b32_e32 v162, 1, v156
	v_ashrrev_i32_e32 v169, 31, v168
	v_ashrrev_i32_e32 v167, 31, v166
	v_ashrrev_i32_e32 v165, 31, v164
	s_cbranch_scc1 .LBB0_642
	s_andn2_b64 vcc, exec, s[20:21]
	s_cbranch_vccz .LBB0_643

.LBB0_642:
	ds_read_b32 v146, v184
	s_lshl_b32 s11, s44, 7
	s_add_i32 s44, s11, 0xfffffe00
	v_lshlrev_b64 v[144:145], 11, v[170:171]
	v_lshl_add_u64 v[144:145], s[40:41], 0, v[144:145]
	s_waitcnt lgkmcnt(0)
	v_pk_fma_f32 v[172:173], v[126:127], v[146:147], v[142:143] op_sel_hi:[1,0,1]
	v_pk_fma_f32 v[186:187], v[124:125], v[146:147], v[140:141] op_sel_hi:[1,0,1]
	v_pk_fma_f32 v[188:189], v[118:119], v[146:147], v[134:135] op_sel_hi:[1,0,1]
	v_pk_fma_f32 v[190:191], v[116:117], v[146:147], v[132:133] op_sel_hi:[1,0,1]
	v_pk_mul_f32 v[172:173], v[172:173], v[188:189]
	v_pk_mul_f32 v[186:187], v[186:187], v[190:191]
	v_pk_fma_f32 v[188:189], v[122:123], v[146:147], v[138:139] op_sel_hi:[1,0,1]
	v_pk_fma_f32 v[190:191], v[120:121], v[146:147], v[136:137] op_sel_hi:[1,0,1]
	v_pk_fma_f32 v[192:193], v[114:115], v[146:147], v[130:131] op_sel_hi:[1,0,1]
	v_pk_fma_f32 v[146:147], v[112:113], v[146:147], v[128:129] op_sel_hi:[1,0,1]
	v_pk_mul_f32 v[192:193], v[188:189], v[192:193]
	v_pk_mul_f32 v[146:147], v[190:191], v[146:147]
	v_cvt_pk_bf16_f32 v186, v186, v187
	v_cvt_pk_bf16_f32 v187, v172, v173
	s_lshl_b64 s[20:21], s[44:45], 1
	v_cvt_pk_bf16_f32 v188, v146, v147
	v_cvt_pk_bf16_f32 v189, v192, v193
	ds_read_b32 v146, v184 offset:64
	v_lshl_add_u64 v[144:145], v[144:145], 0, s[20:21]
	v_mov_b32_e32 v163, v177
	v_lshl_add_u64 v[144:145], v[144:145], 0, v[162:163]
	global_store_dwordx4 v[144:145], v[186:189], off
	s_waitcnt lgkmcnt(0)
	v_pk_fma_f32 v[190:191], v[102:103], v[146:147], v[134:135] op_sel_hi:[1,0,1]
	v_pk_fma_f32 v[192:193], v[100:101], v[146:147], v[132:133] op_sel_hi:[1,0,1]
	v_pk_fma_f32 v[186:187], v[110:111], v[146:147], v[142:143] op_sel_hi:[1,0,1]
	v_pk_fma_f32 v[188:189], v[108:109], v[146:147], v[140:141] op_sel_hi:[1,0,1]
	v_pk_mul_f32 v[190:191], v[186:187], v[190:191]
	v_pk_mul_f32 v[186:187], v[188:189], v[192:193]
	v_pk_fma_f32 v[188:189], v[106:107], v[146:147], v[138:139] op_sel_hi:[1,0,1]
	v_pk_fma_f32 v[192:193], v[104:105], v[146:147], v[136:137] op_sel_hi:[1,0,1]
	v_pk_fma_f32 v[194:195], v[98:99], v[146:147], v[130:131] op_sel_hi:[1,0,1]
	v_pk_fma_f32 v[146:147], v[96:97], v[146:147], v[128:129] op_sel_hi:[1,0,1]
	v_pk_mul_f32 v[194:195], v[188:189], v[194:195]
	v_pk_mul_f32 v[146:147], v[192:193], v[146:147]
	v_cvt_pk_bf16_f32 v186, v186, v187
	v_cvt_pk_bf16_f32 v187, v190, v191
	v_lshlrev_b64 v[172:173], 11, v[168:169]
	v_cvt_pk_bf16_f32 v188, v146, v147
	v_cvt_pk_bf16_f32 v189, v194, v195
	ds_read_b32 v146, v184 offset:128
	v_lshl_add_u64 v[172:173], s[40:41], 0, v[172:173]
	v_lshl_add_u64 v[172:173], v[172:173], 0, s[20:21]
	v_lshl_add_u64 v[172:173], v[172:173], 0, v[162:163]
	global_store_dwordx4 v[172:173], v[186:189], off
	s_waitcnt lgkmcnt(0)
	v_pk_fma_f32 v[190:191], v[86:87], v[146:147], v[134:135] op_sel_hi:[1,0,1]
	v_pk_fma_f32 v[192:193], v[84:85], v[146:147], v[132:133] op_sel_hi:[1,0,1]
	v_pk_fma_f32 v[186:187], v[94:95], v[146:147], v[142:143] op_sel_hi:[1,0,1]
	v_pk_fma_f32 v[188:189], v[92:93], v[146:147], v[140:141] op_sel_hi:[1,0,1]
	v_pk_mul_f32 v[190:191], v[186:187], v[190:191]
	v_pk_mul_f32 v[186:187], v[188:189], v[192:193]
	v_pk_fma_f32 v[188:189], v[90:91], v[146:147], v[138:139] op_sel_hi:[1,0,1]
	v_pk_fma_f32 v[192:193], v[88:89], v[146:147], v[136:137] op_sel_hi:[1,0,1]
	v_pk_fma_f32 v[194:195], v[82:83], v[146:147], v[130:131] op_sel_hi:[1,0,1]
	v_pk_fma_f32 v[146:147], v[80:81], v[146:147], v[128:129] op_sel_hi:[1,0,1]
	v_pk_mul_f32 v[194:195], v[188:189], v[194:195]
	v_pk_mul_f32 v[146:147], v[192:193], v[146:147]
	v_cvt_pk_bf16_f32 v186, v186, v187
	v_cvt_pk_bf16_f32 v187, v190, v191
	v_lshlrev_b64 v[172:173], 11, v[166:167]
	v_cvt_pk_bf16_f32 v188, v146, v147
	v_cvt_pk_bf16_f32 v189, v194, v195
	ds_read_b32 v146, v184 offset:192
	v_lshl_add_u64 v[172:173], s[40:41], 0, v[172:173]
	v_lshl_add_u64 v[172:173], v[172:173], 0, s[20:21]
	v_lshl_add_u64 v[172:173], v[172:173], 0, v[162:163]
	global_store_dwordx4 v[172:173], v[186:189], off
	s_waitcnt lgkmcnt(0)
	v_pk_fma_f32 v[190:191], v[70:71], v[146:147], v[134:135] op_sel_hi:[1,0,1]
	v_pk_fma_f32 v[192:193], v[68:69], v[146:147], v[132:133] op_sel_hi:[1,0,1]
	v_pk_fma_f32 v[186:187], v[78:79], v[146:147], v[142:143] op_sel_hi:[1,0,1]
	v_pk_fma_f32 v[188:189], v[76:77], v[146:147], v[140:141] op_sel_hi:[1,0,1]
	v_pk_mul_f32 v[190:191], v[186:187], v[190:191]
	v_pk_mul_f32 v[186:187], v[188:189], v[192:193]
	v_pk_fma_f32 v[188:189], v[74:75], v[146:147], v[138:139] op_sel_hi:[1,0,1]
	v_pk_fma_f32 v[192:193], v[72:73], v[146:147], v[136:137] op_sel_hi:[1,0,1]
	v_pk_fma_f32 v[194:195], v[66:67], v[146:147], v[130:131] op_sel_hi:[1,0,1]
	v_pk_fma_f32 v[146:147], v[64:65], v[146:147], v[128:129] op_sel_hi:[1,0,1]
	v_pk_mul_f32 v[194:195], v[188:189], v[194:195]
	v_pk_mul_f32 v[146:147], v[192:193], v[146:147]
	v_cvt_pk_bf16_f32 v186, v186, v187
	v_cvt_pk_bf16_f32 v187, v190, v191
	v_lshlrev_b64 v[172:173], 11, v[164:165]
	v_cvt_pk_bf16_f32 v188, v146, v147
	v_cvt_pk_bf16_f32 v189, v194, v195
	ds_read_b32 v146, v184 offset:512
	v_lshl_add_u64 v[172:173], s[40:41], 0, v[172:173]
	v_lshl_add_u64 v[172:173], v[172:173], 0, s[20:21]
	v_lshl_add_u64 v[172:173], v[172:173], 0, v[162:163]
	global_store_dwordx4 v[172:173], v[186:189], off
	s_waitcnt lgkmcnt(0)
	v_pk_fma_f32 v[172:173], v[62:63], v[146:147], v[142:143] op_sel_hi:[1,0,1]
	v_pk_fma_f32 v[190:191], v[52:53], v[146:147], v[132:133] op_sel_hi:[1,0,1]
	v_pk_fma_f32 v[186:187], v[60:61], v[146:147], v[140:141] op_sel_hi:[1,0,1]
	v_pk_fma_f32 v[188:189], v[54:55], v[146:147], v[134:135] op_sel_hi:[1,0,1]
	v_pk_mul_f32 v[186:187], v[186:187], v[190:191]
	v_pk_mul_f32 v[172:173], v[172:173], v[188:189]
	v_pk_fma_f32 v[188:189], v[58:59], v[146:147], v[138:139] op_sel_hi:[1,0,1]
	v_pk_fma_f32 v[190:191], v[56:57], v[146:147], v[136:137] op_sel_hi:[1,0,1]
	v_pk_fma_f32 v[192:193], v[46:47], v[146:147], v[130:131] op_sel_hi:[1,0,1]
	v_pk_fma_f32 v[146:147], v[44:45], v[146:147], v[128:129] op_sel_hi:[1,0,1]
	v_pk_mul_f32 v[192:193], v[188:189], v[192:193]
	v_pk_mul_f32 v[146:147], v[190:191], v[146:147]
	v_cvt_pk_bf16_f32 v186, v186, v187
	v_cvt_pk_bf16_f32 v187, v172, v173
	v_add_co_u32_e32 v172, vcc, s88, v144
	v_cvt_pk_bf16_f32 v188, v146, v147
	v_cvt_pk_bf16_f32 v189, v192, v193
	ds_read_b32 v146, v184 offset:576
	s_nop 0
	v_addc_co_u32_e32 v173, vcc, 0, v145, vcc
	global_store_dwordx4 v[172:173], v[186:189], off
	s_mov_b32 s11, 0x48000
	s_waitcnt lgkmcnt(0)
	v_pk_fma_f32 v[172:173], v[50:51], v[146:147], v[142:143] op_sel_hi:[1,0,1]
	v_pk_fma_f32 v[186:187], v[48:49], v[146:147], v[140:141] op_sel_hi:[1,0,1]
	v_pk_fma_f32 v[188:189], v[38:39], v[146:147], v[134:135] op_sel_hi:[1,0,1]
	v_pk_fma_f32 v[190:191], v[36:37], v[146:147], v[132:133] op_sel_hi:[1,0,1]
	v_pk_mul_f32 v[172:173], v[172:173], v[188:189]
	v_pk_mul_f32 v[186:187], v[186:187], v[190:191]
	v_pk_fma_f32 v[188:189], v[42:43], v[146:147], v[138:139] op_sel_hi:[1,0,1]
	v_pk_fma_f32 v[190:191], v[40:41], v[146:147], v[136:137] op_sel_hi:[1,0,1]
	v_pk_fma_f32 v[192:193], v[30:31], v[146:147], v[130:131] op_sel_hi:[1,0,1]
	v_pk_fma_f32 v[146:147], v[28:29], v[146:147], v[128:129] op_sel_hi:[1,0,1]
	v_pk_mul_f32 v[192:193], v[188:189], v[192:193]
	v_pk_mul_f32 v[146:147], v[190:191], v[146:147]
	v_cvt_pk_bf16_f32 v186, v186, v187
	v_cvt_pk_bf16_f32 v187, v172, v173
	v_add_co_u32_e32 v172, vcc, s11, v144
	v_cvt_pk_bf16_f32 v188, v146, v147
	v_cvt_pk_bf16_f32 v189, v192, v193
	ds_read_b32 v146, v184 offset:640
	s_nop 0
	v_addc_co_u32_e32 v173, vcc, 0, v145, vcc
	global_store_dwordx4 v[172:173], v[186:189], off
	s_mov_b32 s11, 0x50000
	s_waitcnt lgkmcnt(0)
	v_pk_fma_f32 v[172:173], v[34:35], v[146:147], v[142:143] op_sel_hi:[1,0,1]
	v_pk_fma_f32 v[186:187], v[32:33], v[146:147], v[140:141] op_sel_hi:[1,0,1]
	v_pk_fma_f32 v[188:189], v[22:23], v[146:147], v[134:135] op_sel_hi:[1,0,1]
	v_pk_fma_f32 v[190:191], v[20:21], v[146:147], v[132:133] op_sel_hi:[1,0,1]
	v_pk_mul_f32 v[172:173], v[172:173], v[188:189]
	v_pk_mul_f32 v[186:187], v[186:187], v[190:191]
	v_pk_fma_f32 v[188:189], v[26:27], v[146:147], v[138:139] op_sel_hi:[1,0,1]
	v_pk_fma_f32 v[190:191], v[24:25], v[146:147], v[136:137] op_sel_hi:[1,0,1]
	v_pk_fma_f32 v[192:193], v[14:15], v[146:147], v[130:131] op_sel_hi:[1,0,1]
	v_pk_fma_f32 v[146:147], v[12:13], v[146:147], v[128:129] op_sel_hi:[1,0,1]
	v_pk_mul_f32 v[192:193], v[188:189], v[192:193]
	v_pk_mul_f32 v[146:147], v[190:191], v[146:147]
	v_cvt_pk_bf16_f32 v186, v186, v187
	v_cvt_pk_bf16_f32 v187, v172, v173
	v_add_co_u32_e32 v172, vcc, s11, v144
	v_cvt_pk_bf16_f32 v188, v146, v147
	v_cvt_pk_bf16_f32 v189, v192, v193
	ds_read_b32 v146, v184 offset:704
	s_nop 0
	v_addc_co_u32_e32 v173, vcc, 0, v145, vcc
	s_mov_b64 s[20:21], 0x58000
	global_store_dwordx4 v[172:173], v[186:189], off
	v_lshl_add_u64 v[172:173], v[144:145], 0, s[20:21]
	s_waitcnt lgkmcnt(0)
	v_pk_fma_f32 v[144:145], v[18:19], v[146:147], v[142:143] op_sel_hi:[1,0,1]
	v_pk_fma_f32 v[186:187], v[16:17], v[146:147], v[140:141] op_sel_hi:[1,0,1]
	v_pk_fma_f32 v[188:189], v[6:7], v[146:147], v[134:135] op_sel_hi:[1,0,1]
	v_pk_fma_f32 v[190:191], v[4:5], v[146:147], v[132:133] op_sel_hi:[1,0,1]
	v_pk_mul_f32 v[188:189], v[144:145], v[188:189]
	v_pk_mul_f32 v[144:145], v[186:187], v[190:191]
	v_pk_fma_f32 v[186:187], v[10:11], v[146:147], v[138:139] op_sel_hi:[1,0,1]
	v_pk_fma_f32 v[190:191], v[8:9], v[146:147], v[136:137] op_sel_hi:[1,0,1]
	v_pk_fma_f32 v[192:193], v[2:3], v[146:147], v[130:131] op_sel_hi:[1,0,1]
	v_pk_fma_f32 v[146:147], v[0:1], v[146:147], v[128:129] op_sel_hi:[1,0,1]
	v_pk_mul_f32 v[186:187], v[186:187], v[192:193]
	v_pk_mul_f32 v[146:147], v[190:191], v[146:147]
	v_cvt_pk_bf16_f32 v144, v144, v145
	v_cvt_pk_bf16_f32 v145, v188, v189
	s_nop 0
	v_cvt_pk_bf16_f32 v146, v146, v147
	v_cvt_pk_bf16_f32 v147, v186, v187
	s_cbranch_execnz .LBB0_641
.LBB0_643:
	ds_read_b32 v144, v184
	v_lshlrev_b64 v[146:147], 11, v[170:171]
	v_lshl_add_u64 v[146:147], s[38:39], 0, v[146:147]
	s_lshl_b64 s[18:19], s[18:19], 1
	v_lshl_add_u64 v[146:147], v[146:147], 0, s[18:19]
	v_mov_b32_e32 v163, v177
	v_lshl_add_u64 v[170:171], v[146:147], 0, v[162:163]
	s_waitcnt lgkmcnt(0)
	v_pk_fma_f32 v[126:127], v[126:127], v[144:145], v[142:143] op_sel_hi:[1,0,1]
	v_pk_fma_f32 v[124:125], v[124:125], v[144:145], v[140:141] op_sel_hi:[1,0,1]
	v_pk_fma_f32 v[146:147], v[122:123], v[144:145], v[138:139] op_sel_hi:[1,0,1]
	v_pk_fma_f32 v[122:123], v[120:121], v[144:145], v[136:137] op_sel_hi:[1,0,1]
	v_cvt_pk_bf16_f32 v120, v124, v125
	v_cvt_pk_bf16_f32 v121, v126, v127
	v_pk_fma_f32 v[116:117], v[116:117], v[144:145], v[132:133] op_sel_hi:[1,0,1]
	v_cvt_pk_bf16_f32 v122, v122, v123
	v_cvt_pk_bf16_f32 v123, v146, v147
	global_store_dwordx4 v[170:171], v[120:123], off
	v_pk_fma_f32 v[118:119], v[118:119], v[144:145], v[134:135] op_sel_hi:[1,0,1]
	s_mov_b32 s11, 0x48000
	v_pk_fma_f32 v[120:121], v[114:115], v[144:145], v[130:131] op_sel_hi:[1,0,1]
	v_pk_fma_f32 v[114:115], v[112:113], v[144:145], v[128:129] op_sel_hi:[1,0,1]
	v_cvt_pk_bf16_f32 v112, v116, v117
	v_cvt_pk_bf16_f32 v113, v118, v119
	s_nop 0
	v_cvt_pk_bf16_f32 v114, v114, v115
	v_cvt_pk_bf16_f32 v115, v120, v121
	global_store_dwordx4 v[170:171], v[112:115], off offset:256
	ds_read_b32 v112, v184 offset:64
	s_waitcnt lgkmcnt(0)
	v_pk_fma_f32 v[110:111], v[110:111], v[112:113], v[142:143] op_sel_hi:[1,0,1]
	v_lshlrev_b64 v[114:115], 11, v[168:169]
	v_lshl_add_u64 v[114:115], s[38:39], 0, v[114:115]
	v_lshl_add_u64 v[114:115], v[114:115], 0, s[18:19]
	v_lshl_add_u64 v[114:115], v[114:115], 0, v[162:163]
	v_pk_fma_f32 v[108:109], v[108:109], v[112:113], v[140:141] op_sel_hi:[1,0,1]
	v_pk_fma_f32 v[116:117], v[106:107], v[112:113], v[138:139] op_sel_hi:[1,0,1]
	v_pk_fma_f32 v[106:107], v[104:105], v[112:113], v[136:137] op_sel_hi:[1,0,1]
	v_cvt_pk_bf16_f32 v104, v108, v109
	v_cvt_pk_bf16_f32 v105, v110, v111
	v_pk_fma_f32 v[100:101], v[100:101], v[112:113], v[132:133] op_sel_hi:[1,0,1]
	v_cvt_pk_bf16_f32 v106, v106, v107
	v_cvt_pk_bf16_f32 v107, v116, v117
	global_store_dwordx4 v[114:115], v[104:107], off
	v_pk_fma_f32 v[102:103], v[102:103], v[112:113], v[134:135] op_sel_hi:[1,0,1]
	s_nop 0
	v_pk_fma_f32 v[104:105], v[98:99], v[112:113], v[130:131] op_sel_hi:[1,0,1]
	v_pk_fma_f32 v[98:99], v[96:97], v[112:113], v[128:129] op_sel_hi:[1,0,1]
	v_cvt_pk_bf16_f32 v96, v100, v101
	v_cvt_pk_bf16_f32 v97, v102, v103
	s_nop 0
	v_cvt_pk_bf16_f32 v98, v98, v99
	v_cvt_pk_bf16_f32 v99, v104, v105
	global_store_dwordx4 v[114:115], v[96:99], off offset:256
	ds_read_b32 v96, v184 offset:128
	s_waitcnt lgkmcnt(0)
	v_pk_fma_f32 v[94:95], v[94:95], v[96:97], v[142:143] op_sel_hi:[1,0,1]
	v_lshlrev_b64 v[98:99], 11, v[166:167]
	v_lshl_add_u64 v[98:99], s[38:39], 0, v[98:99]
	v_lshl_add_u64 v[98:99], v[98:99], 0, s[18:19]
	v_lshl_add_u64 v[98:99], v[98:99], 0, v[162:163]
	v_pk_fma_f32 v[92:93], v[92:93], v[96:97], v[140:141] op_sel_hi:[1,0,1]
	v_pk_fma_f32 v[100:101], v[90:91], v[96:97], v[138:139] op_sel_hi:[1,0,1]
	v_pk_fma_f32 v[90:91], v[88:89], v[96:97], v[136:137] op_sel_hi:[1,0,1]
	v_cvt_pk_bf16_f32 v88, v92, v93
	v_cvt_pk_bf16_f32 v89, v94, v95
	v_pk_fma_f32 v[84:85], v[84:85], v[96:97], v[132:133] op_sel_hi:[1,0,1]
	v_cvt_pk_bf16_f32 v90, v90, v91
	v_cvt_pk_bf16_f32 v91, v100, v101
	global_store_dwordx4 v[98:99], v[88:91], off
	v_pk_fma_f32 v[86:87], v[86:87], v[96:97], v[134:135] op_sel_hi:[1,0,1]
	s_nop 0
	v_pk_fma_f32 v[88:89], v[82:83], v[96:97], v[130:131] op_sel_hi:[1,0,1]
	v_pk_fma_f32 v[82:83], v[80:81], v[96:97], v[128:129] op_sel_hi:[1,0,1]
	v_cvt_pk_bf16_f32 v80, v84, v85
	v_cvt_pk_bf16_f32 v81, v86, v87
	s_nop 0
	v_cvt_pk_bf16_f32 v82, v82, v83
	v_cvt_pk_bf16_f32 v83, v88, v89
	global_store_dwordx4 v[98:99], v[80:83], off offset:256
	ds_read_b32 v80, v184 offset:192
	s_waitcnt lgkmcnt(0)
	v_pk_fma_f32 v[78:79], v[78:79], v[80:81], v[142:143] op_sel_hi:[1,0,1]
	v_lshlrev_b64 v[82:83], 11, v[164:165]
	v_lshl_add_u64 v[82:83], s[38:39], 0, v[82:83]
	v_lshl_add_u64 v[82:83], v[82:83], 0, s[18:19]
	v_lshl_add_u64 v[82:83], v[82:83], 0, v[162:163]
	v_pk_fma_f32 v[76:77], v[76:77], v[80:81], v[140:141] op_sel_hi:[1,0,1]
	v_pk_fma_f32 v[84:85], v[74:75], v[80:81], v[138:139] op_sel_hi:[1,0,1]
	v_pk_fma_f32 v[74:75], v[72:73], v[80:81], v[136:137] op_sel_hi:[1,0,1]
	v_cvt_pk_bf16_f32 v72, v76, v77
	v_cvt_pk_bf16_f32 v73, v78, v79
	v_pk_fma_f32 v[68:69], v[68:69], v[80:81], v[132:133] op_sel_hi:[1,0,1]
	v_cvt_pk_bf16_f32 v74, v74, v75
	v_cvt_pk_bf16_f32 v75, v84, v85
	global_store_dwordx4 v[82:83], v[72:75], off
	v_pk_fma_f32 v[70:71], v[70:71], v[80:81], v[134:135] op_sel_hi:[1,0,1]
	s_mov_b64 s[18:19], 0x48000
	v_pk_fma_f32 v[72:73], v[66:67], v[80:81], v[130:131] op_sel_hi:[1,0,1]
	v_pk_fma_f32 v[66:67], v[64:65], v[80:81], v[128:129] op_sel_hi:[1,0,1]
	v_cvt_pk_bf16_f32 v64, v68, v69
	v_cvt_pk_bf16_f32 v65, v70, v71
	s_nop 0
	v_cvt_pk_bf16_f32 v66, v66, v67
	v_cvt_pk_bf16_f32 v67, v72, v73
	ds_read_b32 v68, v184 offset:512
	global_store_dwordx4 v[82:83], v[64:67], off offset:256
	s_waitcnt lgkmcnt(0)
	v_pk_fma_f32 v[60:61], v[60:61], v[68:69], v[140:141] op_sel_hi:[1,0,1]
	v_pk_fma_f32 v[64:65], v[58:59], v[68:69], v[138:139] op_sel_hi:[1,0,1]
	v_pk_fma_f32 v[58:59], v[56:57], v[68:69], v[136:137] op_sel_hi:[1,0,1]
	v_cvt_pk_bf16_f32 v56, v60, v61
	v_add_co_u32_e32 v60, vcc, s88, v170
	v_pk_fma_f32 v[62:63], v[62:63], v[68:69], v[142:143] op_sel_hi:[1,0,1]
	s_nop 0
	v_addc_co_u32_e32 v61, vcc, 0, v171, vcc
	v_cvt_pk_bf16_f32 v57, v62, v63
	v_cvt_pk_bf16_f32 v58, v58, v59
	v_cvt_pk_bf16_f32 v59, v64, v65
	global_store_dwordx4 v[60:61], v[56:59], off
	v_pk_fma_f32 v[52:53], v[52:53], v[68:69], v[132:133] op_sel_hi:[1,0,1]
	v_pk_fma_f32 v[54:55], v[54:55], v[68:69], v[134:135] op_sel_hi:[1,0,1]
	v_pk_fma_f32 v[56:57], v[46:47], v[68:69], v[130:131] op_sel_hi:[1,0,1]
	v_pk_fma_f32 v[46:47], v[44:45], v[68:69], v[128:129] op_sel_hi:[1,0,1]
	v_cvt_pk_bf16_f32 v44, v52, v53
	v_cvt_pk_bf16_f32 v45, v54, v55
	v_lshl_add_u64 v[54:55], v[170:171], 0, s[30:31]
	v_cvt_pk_bf16_f32 v46, v46, v47
	v_cvt_pk_bf16_f32 v47, v56, v57
	ds_read_b32 v52, v184 offset:576
	global_store_dwordx4 v[54:55], v[44:47], off offset:256
	s_waitcnt lgkmcnt(0)
	v_pk_fma_f32 v[36:37], v[36:37], v[52:53], v[132:133] op_sel_hi:[1,0,1]
	v_pk_fma_f32 v[44:45], v[50:51], v[52:53], v[142:143] op_sel_hi:[1,0,1]
	v_pk_fma_f32 v[46:47], v[48:49], v[52:53], v[140:141] op_sel_hi:[1,0,1]
	v_pk_fma_f32 v[48:49], v[42:43], v[52:53], v[138:139] op_sel_hi:[1,0,1]
	v_pk_fma_f32 v[42:43], v[40:41], v[52:53], v[136:137] op_sel_hi:[1,0,1]
	v_cvt_pk_bf16_f32 v40, v46, v47
	v_cvt_pk_bf16_f32 v41, v44, v45
	v_add_co_u32_e32 v44, vcc, s11, v170
	v_cvt_pk_bf16_f32 v42, v42, v43
	v_cvt_pk_bf16_f32 v43, v48, v49
	v_pk_fma_f32 v[38:39], v[38:39], v[52:53], v[134:135] op_sel_hi:[1,0,1]
	s_nop 0
	v_addc_co_u32_e32 v45, vcc, 0, v171, vcc
	global_store_dwordx4 v[44:45], v[40:43], off
	s_mov_b32 s11, 0x50000
	s_nop 0
	v_pk_fma_f32 v[40:41], v[30:31], v[52:53], v[130:131] op_sel_hi:[1,0,1]
	v_pk_fma_f32 v[30:31], v[28:29], v[52:53], v[128:129] op_sel_hi:[1,0,1]
	v_cvt_pk_bf16_f32 v28, v36, v37
	v_cvt_pk_bf16_f32 v29, v38, v39
	v_lshl_add_u64 v[38:39], v[170:171], 0, s[18:19]
	v_cvt_pk_bf16_f32 v30, v30, v31
	v_cvt_pk_bf16_f32 v31, v40, v41
	ds_read_b32 v36, v184 offset:640
	global_store_dwordx4 v[38:39], v[28:31], off offset:256
	s_mov_b64 s[18:19], 0x50000
	s_waitcnt lgkmcnt(0)
	v_pk_fma_f32 v[20:21], v[20:21], v[36:37], v[132:133] op_sel_hi:[1,0,1]
	v_pk_fma_f32 v[28:29], v[34:35], v[36:37], v[142:143] op_sel_hi:[1,0,1]
	v_pk_fma_f32 v[30:31], v[32:33], v[36:37], v[140:141] op_sel_hi:[1,0,1]
	v_pk_fma_f32 v[32:33], v[26:27], v[36:37], v[138:139] op_sel_hi:[1,0,1]
	v_pk_fma_f32 v[26:27], v[24:25], v[36:37], v[136:137] op_sel_hi:[1,0,1]
	v_cvt_pk_bf16_f32 v24, v30, v31
	v_cvt_pk_bf16_f32 v25, v28, v29
	v_add_co_u32_e32 v28, vcc, s11, v170
	v_cvt_pk_bf16_f32 v26, v26, v27
	v_cvt_pk_bf16_f32 v27, v32, v33
	v_pk_fma_f32 v[22:23], v[22:23], v[36:37], v[134:135] op_sel_hi:[1,0,1]
	s_nop 0
	v_addc_co_u32_e32 v29, vcc, 0, v171, vcc
	global_store_dwordx4 v[28:29], v[24:27], off
	s_mov_b32 s11, 0x58000
	s_nop 0
	v_pk_fma_f32 v[24:25], v[14:15], v[36:37], v[130:131] op_sel_hi:[1,0,1]
	v_pk_fma_f32 v[14:15], v[12:13], v[36:37], v[128:129] op_sel_hi:[1,0,1]
	v_cvt_pk_bf16_f32 v12, v20, v21
	v_cvt_pk_bf16_f32 v13, v22, v23
	v_lshl_add_u64 v[22:23], v[170:171], 0, s[18:19]
	v_cvt_pk_bf16_f32 v14, v14, v15
	v_cvt_pk_bf16_f32 v15, v24, v25
	ds_read_b32 v20, v184 offset:704
	global_store_dwordx4 v[22:23], v[12:15], off offset:256
	s_mov_b64 s[18:19], 0x58100
	v_lshl_add_u64 v[172:173], v[170:171], 0, s[18:19]
	s_waitcnt lgkmcnt(0)
	v_pk_fma_f32 v[12:13], v[18:19], v[20:21], v[142:143] op_sel_hi:[1,0,1]
	v_pk_fma_f32 v[14:15], v[16:17], v[20:21], v[140:141] op_sel_hi:[1,0,1]
	v_pk_fma_f32 v[16:17], v[10:11], v[20:21], v[138:139] op_sel_hi:[1,0,1]
	v_pk_fma_f32 v[10:11], v[8:9], v[20:21], v[136:137] op_sel_hi:[1,0,1]
	v_cvt_pk_bf16_f32 v8, v14, v15
	v_cvt_pk_bf16_f32 v9, v12, v13
	v_add_co_u32_e32 v12, vcc, s11, v170
	v_cvt_pk_bf16_f32 v10, v10, v11
	v_cvt_pk_bf16_f32 v11, v16, v17
	v_pk_fma_f32 v[6:7], v[6:7], v[20:21], v[134:135] op_sel_hi:[1,0,1]
	s_nop 0
	v_addc_co_u32_e32 v13, vcc, 0, v171, vcc
	global_store_dwordx4 v[12:13], v[8:11], off
	v_pk_fma_f32 v[4:5], v[4:5], v[20:21], v[132:133] op_sel_hi:[1,0,1]
	v_pk_fma_f32 v[2:3], v[2:3], v[20:21], v[130:131] op_sel_hi:[1,0,1]
	v_pk_fma_f32 v[0:1], v[0:1], v[20:21], v[128:129] op_sel_hi:[1,0,1]
	v_cvt_pk_bf16_f32 v144, v4, v5
	v_cvt_pk_bf16_f32 v145, v6, v7
	s_nop 0
	v_cvt_pk_bf16_f32 v146, v0, v1
	v_cvt_pk_bf16_f32 v147, v2, v3
	s_andn2_b64 vcc, exec, s[4:5]
	s_mov_b64 s[4:5], -1
	global_store_dwordx4 v[172:173], v[144:147], off
	s_cbranch_vccnz .LBB0_630
